# QKV GEMM epilogue (non key-norm tiles) rewritten like the SwiGLU one: batched row-scale loads + rsq, in-place scaling, saddr stores
# baseline (speedup 1.0000x reference)
; #define PG8_STAGE(bufoff, gbase, voff) do { _Pragma("unroll") for (int _i = 0; _i < 2; ++_i) \
;         __builtin_amdgcn_global_load_lds((const unsigned*)((const char*)(gbase) + (voff)[_i]), (PG8_LAS unsigned*)(lds + (bufoff) + ldsw + _i * 8192), 16, 0, 0); } while (0)
; #define PG8_LDA(dst, b, h) do { _Pragma("unroll") for (int m = 0; m < 4; ++m) _Pragma("unroll") for (int k = 0; k < 2; ++k) dst[m][k] = *(const PG8_LAS bf16x8*)(lds + PG8_SA(b, h) + aoff + m * 2048 + k * 1024); } while (0)
; #define PG8_LDB(dst, b, h) do { _Pragma("unroll") for (int n = 0; n < 2; ++n) _Pragma("unroll") for (int k = 0; k < 2; ++k) dst[n][k] = *(const PG8_LAS bf16x8*)(lds + PG8_SB(b, h) + boff + n * 2048 + k * 1024); } while (0)
; #define PG8_MMA(ai, bj, At, Bt) do { __builtin_amdgcn_s_setprio(1); _Pragma("unroll") for (int m = 0; m < 4; ++m) _Pragma("unroll") for (int n = 0; n < 2; ++n) _Pragma("unroll") for (int k = 0; k < 2; ++k) \
;         acc[ai][bj][m][n] = __builtin_amdgcn_mfma_f32_16x16x32_bf16(Bt[n][k], At[m][k], acc[ai][bj][m][n], 0, 0, 0); __builtin_amdgcn_s_setprio(0); } while (0)
; #define PG8_WAIT_V(n) asm volatile("s_waitcnt vmcnt(" #n ")" ::: "memory")
; #define PG8_WAIT_L(n) asm volatile("s_waitcnt lgkmcnt(" #n ")" ::: "memory")
; #define PG8_BAR __builtin_amdgcn_s_barrier()
; #define PG8_SCHED __builtin_amdgcn_sched_barrier(0)
; template <class Epi, class Sched, bool ALIGN_EPI = false, bool SP2 = false>
; __device__ __forceinline__ void gemm_phase(PG8_LAS unsigned char* lds, const Gemm g, const Sched& S, const Epi& E) {
;     ...
;             PG8_LDB(B0, 0, 0); PG8_LDB(B1, 0, 1); PG8_SCHED; PG8_LDA(At, 0, 0); PG8_STAGE(PG8_SA(1, 1), a1 + hstep, voffA);
;             PG8_WAIT_V(8); PG8_WAIT_L(0); PG8_BAR; PG8_MMA(0, 0, At, B0); PG8_MMA(0, 1, At, B1); PG8_BAR; PG8_SCHED;
;             PG8_LDA(At, 0, 1); PG8_STAGE(PG8_SB(0, 0), b2, voffB); PG8_STAGE(PG8_SB(0, 1), b2 + hstep, voffB); PG8_STAGE(PG8_SA(0, 0), a2, voffA);
;             PG8_WAIT_V(8); PG8_WAIT_L(0); PG8_BAR; PG8_MMA(1, 0, At, B0); PG8_MMA(1, 1, At, B1); PG8_BAR; PG8_SCHED;
.LBB0_553:
	s_add_u32 s4, s0, 0xfffc0080
	s_addc_u32 s5, s1, -1
	s_add_i32 s14, 0, 0x10000
	s_cmp_eq_u32 s34, 12
	s_cselect_b32 s21, s3, s5
	s_cselect_b32 s20, s10, s4
	s_cselect_b32 s5, s11, s29
	s_cselect_b32 s4, s12, s13
	s_add_i32 s15, 0, 0x14000
	v_add_u32_e32 v166, s14, v151
	v_add_u32_e32 v182, s15, v151
	ds_read_b128 v[142:145], v166
	ds_read_b128 v[146:149], v166 offset:1024
	ds_read_b128 v[162:165], v166 offset:2048
	ds_read_b128 v[166:169], v166 offset:3072
	ds_read_b128 v[170:173], v182
	ds_read_b128 v[174:177], v182 offset:1024
	ds_read_b128 v[178:181], v182 offset:2048
	ds_read_b128 v[182:185], v182 offset:3072
	v_lshl_add_u64 v[190:191], s[0:1], 0, v[138:139]
	s_add_i32 m0, s23, 0xc000
	ds_read_b128 v[186:189], v161
	ds_read_b128 v[200:203], v161 offset:1024
	ds_read_b128 v[206:209], v161 offset:2048
	ds_read_b128 v[210:213], v161 offset:3072
	ds_read_b128 v[224:227], v161 offset:4096
	ds_read_b128 v[228:231], v161 offset:5120
	ds_read_b128 v[232:235], v161 offset:6144
	ds_read_b128 v[236:239], v161 offset:7168
	global_load_lds_dwordx4 v[190:191], off
	v_lshl_add_u64 v[190:191], s[0:1], 0, v[140:141]
	s_add_i32 m0, s23, 0xe000
	s_nop 0
	global_load_lds_dwordx4 v[190:191], off
	s_waitcnt vmcnt(8)
	s_waitcnt lgkmcnt(0)
	s_barrier
	s_setprio 1
	s_waitcnt lgkmcnt(0)
	v_mfma_f32_16x16x32_bf16 v[126:129], v[142:145], v[186:189], v[126:129]
	v_mfma_f32_16x16x32_bf16 v[122:125], v[162:165], v[186:189], v[122:125]
	v_mfma_f32_16x16x32_bf16 v[110:113], v[142:145], v[206:209], v[110:113]
	v_mfma_f32_16x16x32_bf16 v[106:109], v[162:165], v[206:209], v[106:109]
	v_mfma_f32_16x16x32_bf16 v[94:97], v[142:145], v[224:227], v[94:97]
	v_mfma_f32_16x16x32_bf16 v[90:93], v[162:165], v[224:227], v[90:93]
	v_mfma_f32_16x16x32_bf16 v[78:81], v[142:145], v[232:235], v[78:81]
	v_mfma_f32_16x16x32_bf16 v[74:77], v[162:165], v[232:235], v[74:77]
	v_mfma_f32_16x16x32_bf16 v[126:129], v[146:149], v[200:203], v[126:129]
	v_mfma_f32_16x16x32_bf16 v[122:125], v[166:169], v[200:203], v[122:125]
	v_mfma_f32_16x16x32_bf16 v[110:113], v[146:149], v[210:213], v[110:113]
	v_mfma_f32_16x16x32_bf16 v[106:109], v[166:169], v[210:213], v[106:109]
	v_mfma_f32_16x16x32_bf16 v[94:97], v[146:149], v[228:231], v[94:97]
	v_mfma_f32_16x16x32_bf16 v[90:93], v[166:169], v[228:231], v[90:93]
	v_mfma_f32_16x16x32_bf16 v[78:81], v[146:149], v[236:239], v[78:81]
	v_mfma_f32_16x16x32_bf16 v[74:77], v[166:169], v[236:239], v[74:77]
	s_setprio 0
	s_setprio 1
	v_mfma_f32_16x16x32_bf16 v[118:121], v[170:173], v[186:189], v[118:121]
	v_mfma_f32_16x16x32_bf16 v[114:117], v[178:181], v[186:189], v[114:117]
	v_mfma_f32_16x16x32_bf16 v[102:105], v[170:173], v[206:209], v[102:105]
	v_mfma_f32_16x16x32_bf16 v[98:101], v[178:181], v[206:209], v[98:101]
	v_mfma_f32_16x16x32_bf16 v[86:89], v[170:173], v[224:227], v[86:89]
	v_mfma_f32_16x16x32_bf16 v[82:85], v[178:181], v[224:227], v[82:85]
	v_mfma_f32_16x16x32_bf16 v[70:73], v[170:173], v[232:235], v[70:73]
	v_mfma_f32_16x16x32_bf16 v[66:69], v[178:181], v[232:235], v[66:69]
	v_mfma_f32_16x16x32_bf16 v[118:121], v[174:177], v[200:203], v[118:121]
	v_mfma_f32_16x16x32_bf16 v[114:117], v[182:185], v[200:203], v[114:117]
	v_mfma_f32_16x16x32_bf16 v[102:105], v[174:177], v[210:213], v[102:105]
	v_mfma_f32_16x16x32_bf16 v[98:101], v[182:185], v[210:213], v[98:101]
	v_mfma_f32_16x16x32_bf16 v[86:89], v[174:177], v[228:231], v[86:89]
	v_mfma_f32_16x16x32_bf16 v[82:85], v[182:185], v[228:231], v[82:85]
	v_mfma_f32_16x16x32_bf16 v[70:73], v[174:177], v[236:239], v[70:73]
	v_mfma_f32_16x16x32_bf16 v[66:69], v[182:185], v[236:239], v[66:69]
	s_setprio 0
	s_barrier
	s_add_i32 s14, s14, s22
	v_lshl_add_u64 v[190:191], s[4:5], 0, v[0:1]
	s_mov_b32 m0, s14
	ds_read_b128 v[186:189], v161 offset:16384
	ds_read_b128 v[200:203], v161 offset:17408
	ds_read_b128 v[206:209], v161 offset:18432
	ds_read_b128 v[210:213], v161 offset:19456
	ds_read_b128 v[224:227], v161 offset:20480
	ds_read_b128 v[228:231], v161 offset:21504
	ds_read_b128 v[232:235], v161 offset:22528
	ds_read_b128 v[236:239], v161 offset:23552
	global_load_lds_dwordx4 v[190:191], off
	s_add_i32 m0, s14, 0x2000
	s_add_u32 s42, s4, 0x40000
	v_lshl_add_u64 v[192:193], s[4:5], 0, v[130:131]
	s_addc_u32 s43, s5, 0
	s_add_i32 s14, s15, s22
	global_load_lds_dwordx4 v[192:193], off
	v_lshl_add_u64 v[194:195], s[42:43], 0, v[0:1]
	s_mov_b32 m0, s14
	v_lshl_add_u64 v[196:197], s[20:21], 0, v[132:133]
	global_load_lds_dwordx4 v[194:195], off
	v_lshl_add_u64 v[194:195], s[42:43], 0, v[130:131]
	s_add_i32 m0, s14, 0x2000
	s_nop 0
	global_load_lds_dwordx4 v[194:195], off
	v_lshl_add_u64 v[194:195], s[20:21], 0, v[134:135]
	s_mov_b32 m0, s23
	s_nop 0
	global_load_lds_dwordx4 v[194:195], off
	s_mov_b32 m0, s26
	s_nop 0
	global_load_lds_dwordx4 v[196:197], off
	s_waitcnt vmcnt(8)
	s_waitcnt lgkmcnt(0)
	s_barrier
; #define PG8_STAGE(bufoff, gbase, voff) do { _Pragma("unroll") for (int _i = 0; _i < 2; ++_i) \
;         __builtin_amdgcn_global_load_lds((const unsigned*)((const char*)(gbase) + (voff)[_i]), (PG8_LAS unsigned*)(lds + (bufoff) + ldsw + _i * 8192), 16, 0, 0); } while (0)
; #define PG8_LDA(dst, b, h) do { _Pragma("unroll") for (int m = 0; m < 4; ++m) _Pragma("unroll") for (int k = 0; k < 2; ++k) dst[m][k] = *(const PG8_LAS bf16x8*)(lds + PG8_SA(b, h) + aoff + m * 2048 + k * 1024); } while (0)
; #define PG8_LDB(dst, b, h) do { _Pragma("unroll") for (int n = 0; n < 2; ++n) _Pragma("unroll") for (int k = 0; k < 2; ++k) dst[n][k] = *(const PG8_LAS bf16x8*)(lds + PG8_SB(b, h) + boff + n * 2048 + k * 1024); } while (0)
; #define PG8_MMA(ai, bj, At, Bt) do { __builtin_amdgcn_s_setprio(1); _Pragma("unroll") for (int m = 0; m < 4; ++m) _Pragma("unroll") for (int n = 0; n < 2; ++n) _Pragma("unroll") for (int k = 0; k < 2; ++k) \
;         acc[ai][bj][m][n] = __builtin_amdgcn_mfma_f32_16x16x32_bf16(Bt[n][k], At[m][k], acc[ai][bj][m][n], 0, 0, 0); __builtin_amdgcn_s_setprio(0); } while (0)
; #define PG8_WAIT_V(n) asm volatile("s_waitcnt vmcnt(" #n ")" ::: "memory")
; #define PG8_WAIT_L(n) asm volatile("s_waitcnt lgkmcnt(" #n ")" ::: "memory")
; #define PG8_BAR __builtin_amdgcn_s_barrier()
; #define PG8_SCHED __builtin_amdgcn_sched_barrier(0)
; template <class Epi, class Sched, bool ALIGN_EPI = false, bool SP2 = false>
; __device__ __forceinline__ void gemm_phase(PG8_LAS unsigned char* lds, const Gemm g, const Sched& S, const Epi& E) {
;     ...
;             PG8_WAIT_V(8); PG8_WAIT_L(0); PG8_BAR; PG8_MMA(1, 0, At, B0); PG8_MMA(1, 1, At, B1); PG8_BAR; PG8_SCHED;
;             PG8_LDB(B0, 1, 0); PG8_LDB(B1, 1, 1); PG8_SCHED; PG8_LDA(At, 1, 0); PG8_STAGE(PG8_SA(0, 1), a2 + hstep, voffA);
;             PG8_WAIT_V(8); PG8_WAIT_L(0); PG8_BAR; PG8_MMA(0, 0, At, B0); PG8_MMA(0, 1, At, B1); PG8_BAR; PG8_SCHED;
	s_setprio 1
	s_waitcnt lgkmcnt(0)
	v_mfma_f32_16x16x32_bf16 v[62:65], v[142:145], v[186:189], v[62:65]
	v_mfma_f32_16x16x32_bf16 v[58:61], v[162:165], v[186:189], v[58:61]
	v_mfma_f32_16x16x32_bf16 v[46:49], v[142:145], v[206:209], v[46:49]
	v_mfma_f32_16x16x32_bf16 v[42:45], v[162:165], v[206:209], v[42:45]
	v_mfma_f32_16x16x32_bf16 v[30:33], v[142:145], v[224:227], v[30:33]
	v_mfma_f32_16x16x32_bf16 v[26:29], v[162:165], v[224:227], v[26:29]
	v_mfma_f32_16x16x32_bf16 v[14:17], v[142:145], v[232:235], v[14:17]
	v_mfma_f32_16x16x32_bf16 v[10:13], v[162:165], v[232:235], v[10:13]
	v_mfma_f32_16x16x32_bf16 v[62:65], v[146:149], v[200:203], v[62:65]
	v_mfma_f32_16x16x32_bf16 v[58:61], v[166:169], v[200:203], v[58:61]
	v_mfma_f32_16x16x32_bf16 v[46:49], v[146:149], v[210:213], v[46:49]
	v_mfma_f32_16x16x32_bf16 v[42:45], v[166:169], v[210:213], v[42:45]
	v_mfma_f32_16x16x32_bf16 v[30:33], v[146:149], v[228:231], v[30:33]
	v_mfma_f32_16x16x32_bf16 v[26:29], v[166:169], v[228:231], v[26:29]
	v_mfma_f32_16x16x32_bf16 v[14:17], v[146:149], v[236:239], v[14:17]
	v_mfma_f32_16x16x32_bf16 v[10:13], v[166:169], v[236:239], v[10:13]
	s_setprio 0
	s_setprio 1
	v_mfma_f32_16x16x32_bf16 v[54:57], v[170:173], v[186:189], v[54:57]
	v_mfma_f32_16x16x32_bf16 v[50:53], v[178:181], v[186:189], v[50:53]
	v_mfma_f32_16x16x32_bf16 v[38:41], v[170:173], v[206:209], v[38:41]
	v_mfma_f32_16x16x32_bf16 v[34:37], v[178:181], v[206:209], v[34:37]
	v_mfma_f32_16x16x32_bf16 v[22:25], v[170:173], v[224:227], v[22:25]
	v_mfma_f32_16x16x32_bf16 v[18:21], v[178:181], v[224:227], v[18:21]
	v_mfma_f32_16x16x32_bf16 v[6:9], v[170:173], v[232:235], v[6:9]
	v_mfma_f32_16x16x32_bf16 v[2:5], v[178:181], v[232:235], v[2:5]
	v_mfma_f32_16x16x32_bf16 v[54:57], v[174:177], v[200:203], v[54:57]
	v_mfma_f32_16x16x32_bf16 v[50:53], v[182:185], v[200:203], v[50:53]
	v_mfma_f32_16x16x32_bf16 v[38:41], v[174:177], v[210:213], v[38:41]
	v_mfma_f32_16x16x32_bf16 v[34:37], v[182:185], v[210:213], v[34:37]
	v_mfma_f32_16x16x32_bf16 v[22:25], v[174:177], v[228:231], v[22:25]
	v_mfma_f32_16x16x32_bf16 v[18:21], v[182:185], v[228:231], v[18:21]
	v_mfma_f32_16x16x32_bf16 v[6:9], v[174:177], v[236:239], v[6:9]
	v_mfma_f32_16x16x32_bf16 v[2:5], v[182:185], v[236:239], v[2:5]
	s_setprio 0
	s_barrier
	s_add_i32 s14, 0, 0x18000
	s_add_i32 s15, 0, 0x1c000
	v_add_u32_e32 v166, s14, v151
	v_add_u32_e32 v182, s15, v151
	ds_read_b128 v[142:145], v166
	ds_read_b128 v[146:149], v166 offset:1024
	ds_read_b128 v[162:165], v166 offset:2048
	ds_read_b128 v[166:169], v166 offset:3072
	ds_read_b128 v[170:173], v182
	ds_read_b128 v[174:177], v182 offset:1024
	ds_read_b128 v[178:181], v182 offset:2048
	ds_read_b128 v[182:185], v182 offset:3072
	s_add_u32 s20, s20, 0x40000
	s_addc_u32 s21, s21, 0
	s_mov_b32 m0, s30
	v_lshl_add_u64 v[198:199], s[20:21], 0, v[134:135]
	ds_read_b128 v[186:189], v161 offset:32768
	ds_read_b128 v[200:203], v161 offset:33792
	ds_read_b128 v[206:209], v161 offset:34816
	ds_read_b128 v[210:213], v161 offset:35840
	ds_read_b128 v[224:227], v161 offset:36864
	ds_read_b128 v[228:231], v161 offset:37888
	ds_read_b128 v[232:235], v161 offset:38912
	ds_read_b128 v[236:239], v161 offset:39936
	global_load_lds_dwordx4 v[198:199], off
	v_lshl_add_u64 v[198:199], s[20:21], 0, v[132:133]
	s_mov_b32 m0, s31
	s_nop 0
	global_load_lds_dwordx4 v[198:199], off
	s_waitcnt vmcnt(8)
	s_waitcnt lgkmcnt(0)
	s_barrier
	s_setprio 1
	s_waitcnt lgkmcnt(0)
	v_mfma_f32_16x16x32_bf16 v[126:129], v[142:145], v[186:189], v[126:129]
	v_mfma_f32_16x16x32_bf16 v[122:125], v[162:165], v[186:189], v[122:125]
	v_mfma_f32_16x16x32_bf16 v[110:113], v[142:145], v[206:209], v[110:113]
	v_mfma_f32_16x16x32_bf16 v[106:109], v[162:165], v[206:209], v[106:109]
	v_mfma_f32_16x16x32_bf16 v[94:97], v[142:145], v[224:227], v[94:97]
	v_mfma_f32_16x16x32_bf16 v[90:93], v[162:165], v[224:227], v[90:93]
	v_mfma_f32_16x16x32_bf16 v[78:81], v[142:145], v[232:235], v[78:81]
	v_mfma_f32_16x16x32_bf16 v[74:77], v[162:165], v[232:235], v[74:77]
	v_mfma_f32_16x16x32_bf16 v[126:129], v[146:149], v[200:203], v[126:129]
	v_mfma_f32_16x16x32_bf16 v[122:125], v[166:169], v[200:203], v[122:125]
	v_mfma_f32_16x16x32_bf16 v[110:113], v[146:149], v[210:213], v[110:113]
	v_mfma_f32_16x16x32_bf16 v[106:109], v[166:169], v[210:213], v[106:109]
	v_mfma_f32_16x16x32_bf16 v[94:97], v[146:149], v[228:231], v[94:97]
	v_mfma_f32_16x16x32_bf16 v[90:93], v[166:169], v[228:231], v[90:93]
	v_mfma_f32_16x16x32_bf16 v[78:81], v[146:149], v[236:239], v[78:81]
	v_mfma_f32_16x16x32_bf16 v[74:77], v[166:169], v[236:239], v[74:77]
	s_setprio 0
	s_setprio 1
	v_mfma_f32_16x16x32_bf16 v[118:121], v[170:173], v[186:189], v[118:121]
	v_mfma_f32_16x16x32_bf16 v[114:117], v[178:181], v[186:189], v[114:117]
	v_mfma_f32_16x16x32_bf16 v[102:105], v[170:173], v[206:209], v[102:105]
	v_mfma_f32_16x16x32_bf16 v[98:101], v[178:181], v[206:209], v[98:101]
	v_mfma_f32_16x16x32_bf16 v[86:89], v[170:173], v[224:227], v[86:89]
	v_mfma_f32_16x16x32_bf16 v[82:85], v[178:181], v[224:227], v[82:85]
	v_mfma_f32_16x16x32_bf16 v[70:73], v[170:173], v[232:235], v[70:73]
	v_mfma_f32_16x16x32_bf16 v[66:69], v[178:181], v[232:235], v[66:69]
	v_mfma_f32_16x16x32_bf16 v[118:121], v[174:177], v[200:203], v[118:121]
	v_mfma_f32_16x16x32_bf16 v[114:117], v[182:185], v[200:203], v[114:117]
	v_mfma_f32_16x16x32_bf16 v[102:105], v[174:177], v[210:213], v[102:105]
	v_mfma_f32_16x16x32_bf16 v[98:101], v[182:185], v[210:213], v[98:101]
	v_mfma_f32_16x16x32_bf16 v[86:89], v[174:177], v[228:231], v[86:89]
	v_mfma_f32_16x16x32_bf16 v[82:85], v[182:185], v[228:231], v[82:85]
	v_mfma_f32_16x16x32_bf16 v[70:73], v[174:177], v[236:239], v[70:73]
	v_mfma_f32_16x16x32_bf16 v[66:69], v[182:185], v[236:239], v[66:69]
	s_setprio 0
	s_barrier
; #define PG8_STAGE(bufoff, gbase, voff) do { _Pragma("unroll") for (int _i = 0; _i < 2; ++_i) \
;         __builtin_amdgcn_global_load_lds((const unsigned*)((const char*)(gbase) + (voff)[_i]), (PG8_LAS unsigned*)(lds + (bufoff) + ldsw + _i * 8192), 16, 0, 0); } while (0)
; #define PG8_LDA(dst, b, h) do { _Pragma("unroll") for (int m = 0; m < 4; ++m) _Pragma("unroll") for (int k = 0; k < 2; ++k) dst[m][k] = *(const PG8_LAS bf16x8*)(lds + PG8_SA(b, h) + aoff + m * 2048 + k * 1024); } while (0)
; #define PG8_MMA(ai, bj, At, Bt) do { __builtin_amdgcn_s_setprio(1); _Pragma("unroll") for (int m = 0; m < 4; ++m) _Pragma("unroll") for (int n = 0; n < 2; ++n) _Pragma("unroll") for (int k = 0; k < 2; ++k) \
;         acc[ai][bj][m][n] = __builtin_amdgcn_mfma_f32_16x16x32_bf16(Bt[n][k], At[m][k], acc[ai][bj][m][n], 0, 0, 0); __builtin_amdgcn_s_setprio(0); } while (0)
; #define PG8_BAR __builtin_amdgcn_s_barrier()
; template <class Epi, class Sched, bool ALIGN_EPI = false, bool SP2 = false>
; __device__ __forceinline__ void gemm_phase(PG8_LAS unsigned char* lds, const Gemm g, const Sched& S, const Epi& E) {
;     ...
;             PG8_LDA(At, 1, 1); PG8_STAGE(PG8_SB(1, 0), b3, voffB); PG8_STAGE(PG8_SB(1, 1), b3 + hstep, voffB); PG8_STAGE(PG8_SA(1, 0), a3, voffA);
;             PG8_WAIT_V(8); PG8_WAIT_L(0); PG8_BAR; PG8_MMA(1, 0, At, B0); PG8_MMA(1, 1, At, B1); PG8_BAR; PG8_SCHED;
; __device__ __forceinline__ float row_rs(const float* ss, int row, int fq, int fr) {
;     ...
;     return 1.0f;
;     ...
;     const f32x4 a = *(const f32x4*)(ss + (size_t)row * 16 + 4 * fq);
;     float s = (a[0] + a[1]) + (a[2] + a[3]);
;     const int ln = fq * 16 + fr; s += sx(s, 16, ln); s += sx(s, 32, ln);
;     return 1.0f / sqrtf(s * (1.0f / D) + RMS_EPS);
; }
;     __device__ __forceinline__ void operator()(const f32x4 (&acc)[2][2][4][2], const Unit& u, int wr, int wc, int fr, int fq) const {
;         const int row0 = u.pm * BM + wr * 64 + fr, col0 = u.pn * BM + wc * 32 + 8 * fq;
;         const float qs = ((qmask >> u.pn) & 1u) ? QSCALE : 1.0f;
;         const bool kt = kn2 != nullptr && u.pn >= 4 && u.pn < 8;
;         const int ln = fq * 16 + fr;
;         float km[2][2] = {{0.f, 0.f}, {0.f, 0.f}};
; #pragma unroll
;         for (int ai = 0; ai < 2; ++ai)
; #pragma unroll
;             for (int m = 0; m < 4; ++m) { const int row = row0 + ai * HALF + m * 16; const float rs = row_rs(ss, row, fq, fr) * qs;
	s_add_i32 s14, s14, s22
	v_lshl_add_u64 v[190:191], v[190:191], 0, s[24:25]
	s_mov_b32 m0, s14
	ds_read_b128 v[186:189], v161 offset:49152
	ds_read_b128 v[200:203], v161 offset:50176
	ds_read_b128 v[206:209], v161 offset:51200
	ds_read_b128 v[210:213], v161 offset:52224
	ds_read_b128 v[224:227], v161 offset:53248
	ds_read_b128 v[228:231], v161 offset:54272
	ds_read_b128 v[232:235], v161 offset:55296
	ds_read_b128 v[236:239], v161 offset:56320
	global_load_lds_dwordx4 v[190:191], off
	s_add_i32 m0, s14, 0x2000
	s_add_u32 s4, s4, 0x40080
	v_lshl_add_u64 v[190:191], v[192:193], 0, s[24:25]
	s_addc_u32 s5, s5, 0
	s_add_i32 s14, s15, s22
	global_load_lds_dwordx4 v[190:191], off
	v_lshl_add_u64 v[190:191], s[4:5], 0, v[0:1]
	s_mov_b32 m0, s14
	s_nop 0
	global_load_lds_dwordx4 v[190:191], off
	v_lshl_add_u64 v[190:191], s[4:5], 0, v[130:131]
	s_add_i32 m0, s14, 0x2000
	s_nop 0
	global_load_lds_dwordx4 v[190:191], off
	v_lshl_add_u64 v[190:191], v[194:195], 0, s[24:25]
	s_mov_b32 m0, s56
	s_nop 0
	global_load_lds_dwordx4 v[190:191], off
	v_lshl_add_u64 v[190:191], v[196:197], 0, s[24:25]
	s_mov_b32 m0, s57
	s_nop 0
	global_load_lds_dwordx4 v[190:191], off
	s_waitcnt vmcnt(8)
	s_waitcnt lgkmcnt(0)
	s_barrier
	s_setprio 1
	s_waitcnt lgkmcnt(0)
	v_mfma_f32_16x16x32_bf16 v[62:65], v[142:145], v[186:189], v[62:65]
	v_mfma_f32_16x16x32_bf16 v[58:61], v[162:165], v[186:189], v[58:61]
	v_mfma_f32_16x16x32_bf16 v[46:49], v[142:145], v[206:209], v[46:49]
	v_mfma_f32_16x16x32_bf16 v[42:45], v[162:165], v[206:209], v[42:45]
	v_mfma_f32_16x16x32_bf16 v[30:33], v[142:145], v[224:227], v[30:33]
	v_mfma_f32_16x16x32_bf16 v[26:29], v[162:165], v[224:227], v[26:29]
	v_mfma_f32_16x16x32_bf16 v[14:17], v[142:145], v[232:235], v[14:17]
	v_mfma_f32_16x16x32_bf16 v[10:13], v[162:165], v[232:235], v[10:13]
	v_mfma_f32_16x16x32_bf16 v[62:65], v[146:149], v[200:203], v[62:65]
	v_mfma_f32_16x16x32_bf16 v[58:61], v[166:169], v[200:203], v[58:61]
	v_mfma_f32_16x16x32_bf16 v[46:49], v[146:149], v[210:213], v[46:49]
	v_mfma_f32_16x16x32_bf16 v[42:45], v[166:169], v[210:213], v[42:45]
	v_mfma_f32_16x16x32_bf16 v[30:33], v[146:149], v[228:231], v[30:33]
	v_mfma_f32_16x16x32_bf16 v[26:29], v[166:169], v[228:231], v[26:29]
	v_mfma_f32_16x16x32_bf16 v[14:17], v[146:149], v[236:239], v[14:17]
	v_mfma_f32_16x16x32_bf16 v[10:13], v[166:169], v[236:239], v[10:13]
	s_setprio 0
	s_setprio 1
	v_mfma_f32_16x16x32_bf16 v[54:57], v[170:173], v[186:189], v[54:57]
	v_mfma_f32_16x16x32_bf16 v[50:53], v[178:181], v[186:189], v[50:53]
	v_mfma_f32_16x16x32_bf16 v[38:41], v[170:173], v[206:209], v[38:41]
	v_mfma_f32_16x16x32_bf16 v[34:37], v[178:181], v[206:209], v[34:37]
	v_mfma_f32_16x16x32_bf16 v[22:25], v[170:173], v[224:227], v[22:25]
	v_mfma_f32_16x16x32_bf16 v[18:21], v[178:181], v[224:227], v[18:21]
	v_mfma_f32_16x16x32_bf16 v[6:9], v[170:173], v[232:235], v[6:9]
	v_mfma_f32_16x16x32_bf16 v[2:5], v[178:181], v[232:235], v[2:5]
	v_mfma_f32_16x16x32_bf16 v[54:57], v[174:177], v[200:203], v[54:57]
	v_mfma_f32_16x16x32_bf16 v[50:53], v[182:185], v[200:203], v[50:53]
	v_mfma_f32_16x16x32_bf16 v[38:41], v[174:177], v[210:213], v[38:41]
	v_mfma_f32_16x16x32_bf16 v[34:37], v[182:185], v[210:213], v[34:37]
	v_mfma_f32_16x16x32_bf16 v[22:25], v[174:177], v[228:231], v[22:25]
	v_mfma_f32_16x16x32_bf16 v[18:21], v[182:185], v[228:231], v[18:21]
	v_mfma_f32_16x16x32_bf16 v[6:9], v[174:177], v[236:239], v[6:9]
	v_mfma_f32_16x16x32_bf16 v[2:5], v[182:185], v[236:239], v[2:5]
	s_setprio 0
	s_barrier
	s_add_i32 s34, s34, 2
	s_add_u32 s0, s0, 0x100
	s_addc_u32 s1, s1, 0
	s_add_u32 s13, s13, 0x100
	s_addc_u32 s29, s29, 0
	s_cmp_gt_u32 s34, 13
	s_cbranch_scc0 .LBB0_553
	s_and_b32 s1, s60, -4
	s_cmp_eq_u32 s1, 4
	s_cselect_b64 s[4:5], -1, 0
	s_and_b64 s[4:5], s[8:9], s[4:5]
	s_cbranch_scc1 .Lqkv_old
	s_lshl_b32 s0, s2, 8
	v_add_u32_e32 v144, s0, v150
	v_ashrrev_i32_e32 v145, 31, v144
	v_lshlrev_b64 v[146:147], 6, v[144:145]
	s_mov_b32 s4, 0x2000
	s_mov_b32 s5, 0
	v_lshl_add_u64 v[146:147], v[136:137], 0, v[146:147]
	v_lshl_add_u64 v[148:149], v[146:147], 0, s[4:5]
	global_load_dwordx4 v[162:165], v[146:147], off
	global_load_dwordx4 v[166:169], v[146:147], off offset:1024
	global_load_dwordx4 v[170:173], v[146:147], off offset:2048
	global_load_dwordx4 v[174:177], v[146:147], off offset:3072
	global_load_dwordx4 v[178:181], v[148:149], off
	global_load_dwordx4 v[182:185], v[148:149], off offset:1024
	global_load_dwordx4 v[186:189], v[148:149], off offset:2048
	global_load_dwordx4 v[190:193], v[148:149], off offset:3072
	s_lshr_b32 s1, s55, s60
	s_bitcmp0_b32 s1, 0
	s_cselect_b64 s[4:5], -1, 0
	v_cndmask_b32_e64 v202, v204, 1.0, s[4:5]
	v_lshl_or_b32 v142, s60, 8, v152
	v_mul_u32_u24_e32 v232, 0x1800, v144
	v_lshl_add_u32 v232, v142, 1, v232
	s_waitcnt vmcnt(7)
	v_add_f32_e32 v163, v163, v162
	v_add_f32_e32 v164, v164, v165
	s_waitcnt vmcnt(6)
	v_add_f32_e32 v167, v167, v166
	v_add_f32_e32 v168, v168, v169
	s_waitcnt vmcnt(5)
	v_add_f32_e32 v171, v171, v170
	v_add_f32_e32 v172, v172, v173
	s_waitcnt vmcnt(4)
	v_add_f32_e32 v175, v175, v174
	v_add_f32_e32 v176, v176, v177
	s_waitcnt vmcnt(3)
	v_add_f32_e32 v179, v179, v178
	v_add_f32_e32 v180, v180, v181
	s_waitcnt vmcnt(2)
	v_add_f32_e32 v183, v183, v182
	v_add_f32_e32 v184, v184, v185
	s_waitcnt vmcnt(1)
	v_add_f32_e32 v187, v187, v186
	v_add_f32_e32 v188, v188, v189
	s_waitcnt vmcnt(0)
; __device__ __forceinline__ unsigned cvt_pk_bf16(float lo, float hi) { unsigned r; asm volatile("v_cvt_pk_bf16_f32 %0, %1, %2" : "=v"(r) : "v"(lo), "v"(hi)); return r; }
; __device__ __forceinline__ float sx(float v, int mask, int lane) { return __int_as_float(__builtin_amdgcn_ds_bpermute((lane ^ mask) << 2, __float_as_int(v))); }
; __device__ __forceinline__ float row_rs(const float* ss, int row, int fq, int fr) {
;     ...
;     const f32x4 a = *(const f32x4*)(ss + (size_t)row * 16 + 4 * fq);
;     float s = (a[0] + a[1]) + (a[2] + a[3]);
;     const int ln = fq * 16 + fr; s += sx(s, 16, ln); s += sx(s, 32, ln);
;     return 1.0f / sqrtf(s * (1.0f / D) + RMS_EPS);
; }
;     __device__ __forceinline__ void operator()(const f32x4 (&acc)[2][2][4][2], const Unit& u, int wr, int wc, int fr, int fq) const {
;         const int row0 = u.pm * BM + wr * 64 + fr, col0 = u.pn * BM + wc * 32 + 8 * fq;
;         const float qs = ((qmask >> u.pn) & 1u) ? QSCALE : 1.0f;
;         const bool kt = kn2 != nullptr && u.pn >= 4 && u.pn < 8;
;         const int ln = fq * 16 + fr;
;         float km[2][2] = {{0.f, 0.f}, {0.f, 0.f}};
; #pragma unroll
;         for (int ai = 0; ai < 2; ++ai)
; #pragma unroll
;             for (int m = 0; m < 4; ++m) { const int row = row0 + ai * HALF + m * 16; const float rs = row_rs(ss, row, fq, fr) * qs;
;                 bf16_t* rowp = O + (size_t)row * ldc + col0;
; #pragma unroll
;                 for (int bj = 0; bj < 2; ++bj) { const f32x4 v0 = acc[ai][bj][m][0] * rs, v1 = acc[ai][bj][m][1] * rs;
;                     u32x4 w; w.x = cvt_pk_bf16(v0[0], v0[1]); w.y = cvt_pk_bf16(v0[2], v0[3]); w.z = cvt_pk_bf16(v1[0], v1[1]); w.w = cvt_pk_bf16(v1[2], v1[3]);
;                     *(u32x4*)(rowp + bj * HALF) = w;
	v_add_f32_e32 v191, v191, v190
	v_add_f32_e32 v192, v192, v193
	v_add_f32_e32 v162, v163, v164
	v_add_f32_e32 v166, v167, v168
	v_add_f32_e32 v170, v171, v172
	v_add_f32_e32 v174, v175, v176
	v_add_f32_e32 v178, v179, v180
	v_add_f32_e32 v182, v183, v184
	v_add_f32_e32 v186, v187, v188
	v_add_f32_e32 v190, v191, v192
	ds_bpermute_b32 v163, v153, v162
	ds_bpermute_b32 v167, v153, v166
	ds_bpermute_b32 v171, v153, v170
	ds_bpermute_b32 v175, v153, v174
	ds_bpermute_b32 v179, v153, v178
	ds_bpermute_b32 v183, v153, v182
	ds_bpermute_b32 v187, v153, v186
	ds_bpermute_b32 v191, v153, v190
	s_waitcnt lgkmcnt(7)
	v_add_f32_e32 v162, v162, v163
	s_waitcnt lgkmcnt(6)
	v_add_f32_e32 v166, v166, v167
	s_waitcnt lgkmcnt(5)
	v_add_f32_e32 v170, v170, v171
	s_waitcnt lgkmcnt(4)
	v_add_f32_e32 v174, v174, v175
	s_waitcnt lgkmcnt(3)
	v_add_f32_e32 v178, v178, v179
	s_waitcnt lgkmcnt(2)
	v_add_f32_e32 v182, v182, v183
	s_waitcnt lgkmcnt(1)
	v_add_f32_e32 v186, v186, v187
	s_waitcnt lgkmcnt(0)
	v_add_f32_e32 v190, v190, v191
	ds_bpermute_b32 v163, v154, v162
	ds_bpermute_b32 v167, v154, v166
	ds_bpermute_b32 v171, v154, v170
	ds_bpermute_b32 v175, v154, v174
	ds_bpermute_b32 v179, v154, v178
	ds_bpermute_b32 v183, v154, v182
	ds_bpermute_b32 v187, v154, v186
	ds_bpermute_b32 v191, v154, v190
	s_waitcnt lgkmcnt(7)
	v_add_f32_e32 v162, v162, v163
	s_waitcnt lgkmcnt(6)
	v_add_f32_e32 v166, v166, v167
	s_waitcnt lgkmcnt(5)
	v_add_f32_e32 v170, v170, v171
	s_waitcnt lgkmcnt(4)
	v_add_f32_e32 v174, v174, v175
	s_waitcnt lgkmcnt(3)
	v_add_f32_e32 v178, v178, v179
	s_waitcnt lgkmcnt(2)
	v_add_f32_e32 v182, v182, v183
	s_waitcnt lgkmcnt(1)
	v_add_f32_e32 v186, v186, v187
	s_waitcnt lgkmcnt(0)
	v_add_f32_e32 v190, v190, v191
	v_fmamk_f32 v162, v162, 0x3a800000, v215
	v_fmamk_f32 v166, v166, 0x3a800000, v215
	v_fmamk_f32 v170, v170, 0x3a800000, v215
	v_fmamk_f32 v174, v174, 0x3a800000, v215
	v_fmamk_f32 v178, v178, 0x3a800000, v215
	v_fmamk_f32 v182, v182, 0x3a800000, v215
	v_fmamk_f32 v186, v186, 0x3a800000, v215
	v_fmamk_f32 v190, v190, 0x3a800000, v215
	v_rsq_f32_e32 v194, v162
	v_rsq_f32_e32 v195, v166
	v_rsq_f32_e32 v196, v170
	v_rsq_f32_e32 v197, v174
	v_rsq_f32_e32 v198, v178
	v_rsq_f32_e32 v199, v182
	v_rsq_f32_e32 v200, v186
	v_rsq_f32_e32 v201, v190
	v_mul_f32_e32 v194, v202, v194
	v_mul_f32_e32 v195, v202, v195
	v_mul_f32_e32 v196, v202, v196
	v_mul_f32_e32 v197, v202, v197
	v_mul_f32_e32 v198, v202, v198
	v_mul_f32_e32 v199, v202, v199
	v_mul_f32_e32 v200, v202, v200
	v_mul_f32_e32 v201, v202, v201
	s_and_b64 vcc, exec, s[44:45]
	s_cbranch_vccz .Lqkv_nobar
	s_barrier
.Lqkv_nobar:
	v_mul_f32_e32 v126, v126, v194
	v_mul_f32_e32 v127, v127, v194
	v_mul_f32_e32 v128, v128, v194
	v_mul_f32_e32 v129, v129, v194
	v_mul_f32_e32 v122, v122, v194
	v_mul_f32_e32 v123, v123, v194
	v_mul_f32_e32 v124, v124, v194
	v_mul_f32_e32 v125, v125, v194
	v_mul_f32_e32 v118, v118, v194
	v_mul_f32_e32 v119, v119, v194
	v_mul_f32_e32 v120, v120, v194
	v_mul_f32_e32 v121, v121, v194
	v_mul_f32_e32 v114, v114, v194
	v_mul_f32_e32 v115, v115, v194
	v_mul_f32_e32 v116, v116, v194
	v_mul_f32_e32 v117, v117, v194
	v_add_u32_e32 v233, 0x18000, v232
	v_cvt_pk_bf16_f32 v206, v126, v127
	v_cvt_pk_bf16_f32 v207, v128, v129
	v_cvt_pk_bf16_f32 v208, v122, v123
	v_cvt_pk_bf16_f32 v209, v124, v125
	v_cvt_pk_bf16_f32 v210, v118, v119
	v_cvt_pk_bf16_f32 v211, v120, v121
	v_cvt_pk_bf16_f32 v212, v114, v115
	v_cvt_pk_bf16_f32 v213, v116, v117
	global_store_dwordx4 v232, v[206:209], s[94:95]
	global_store_dwordx4 v232, v[210:213], s[94:95] offset:256
	v_mul_f32_e32 v110, v110, v195
	v_mul_f32_e32 v111, v111, v195
	v_mul_f32_e32 v112, v112, v195
	v_mul_f32_e32 v113, v113, v195
	v_mul_f32_e32 v106, v106, v195
	v_mul_f32_e32 v107, v107, v195
	v_mul_f32_e32 v108, v108, v195
	v_mul_f32_e32 v109, v109, v195
	v_mul_f32_e32 v102, v102, v195
	v_mul_f32_e32 v103, v103, v195
	v_mul_f32_e32 v104, v104, v195
	v_mul_f32_e32 v105, v105, v195
	v_mul_f32_e32 v98, v98, v195
	v_mul_f32_e32 v99, v99, v195
	v_mul_f32_e32 v100, v100, v195
	v_mul_f32_e32 v101, v101, v195
	v_add_u32_e32 v232, 0x18000, v233
	v_cvt_pk_bf16_f32 v224, v110, v111
	v_cvt_pk_bf16_f32 v225, v112, v113
	v_cvt_pk_bf16_f32 v226, v106, v107
	v_cvt_pk_bf16_f32 v227, v108, v109
	v_cvt_pk_bf16_f32 v228, v102, v103
	v_cvt_pk_bf16_f32 v229, v104, v105
	v_cvt_pk_bf16_f32 v230, v98, v99
	v_cvt_pk_bf16_f32 v231, v100, v101
	global_store_dwordx4 v233, v[224:227], s[94:95]
	global_store_dwordx4 v233, v[228:231], s[94:95] offset:256
	v_mul_f32_e32 v94, v94, v196
	v_mul_f32_e32 v95, v95, v196
	v_mul_f32_e32 v96, v96, v196
	v_mul_f32_e32 v97, v97, v196
	v_mul_f32_e32 v90, v90, v196
	v_mul_f32_e32 v91, v91, v196
	v_mul_f32_e32 v92, v92, v196
	v_mul_f32_e32 v93, v93, v196
	v_mul_f32_e32 v86, v86, v196
	v_mul_f32_e32 v87, v87, v196
	v_mul_f32_e32 v88, v88, v196
	v_mul_f32_e32 v89, v89, v196
	v_mul_f32_e32 v82, v82, v196
	v_mul_f32_e32 v83, v83, v196
	v_mul_f32_e32 v84, v84, v196
	v_mul_f32_e32 v85, v85, v196
; __device__ __forceinline__ unsigned cvt_pk_bf16(float lo, float hi) { unsigned r; asm volatile("v_cvt_pk_bf16_f32 %0, %1, %2" : "=v"(r) : "v"(lo), "v"(hi)); return r; }
; __device__ __forceinline__ float sx(float v, int mask, int lane) { return __int_as_float(__builtin_amdgcn_ds_bpermute((lane ^ mask) << 2, __float_as_int(v))); }
;     __device__ __forceinline__ void operator()(const f32x4 (&acc)[2][2][4][2], const Unit& u, int wr, int wc, int fr, int fq) const {
;     ...
;             for (int m = 0; m < 4; ++m) { const int row = row0 + ai * HALF + m * 16; const float rs = row_rs(ss, row, fq, fr) * qs;
;                 bf16_t* rowp = O + (size_t)row * ldc + col0;
; #pragma unroll
;                 for (int bj = 0; bj < 2; ++bj) { const f32x4 v0 = acc[ai][bj][m][0] * rs, v1 = acc[ai][bj][m][1] * rs;
;                     u32x4 w; w.x = cvt_pk_bf16(v0[0], v0[1]); w.y = cvt_pk_bf16(v0[2], v0[3]); w.z = cvt_pk_bf16(v1[0], v1[1]); w.w = cvt_pk_bf16(v1[2], v1[3]);
;                     *(u32x4*)(rowp + bj * HALF) = w;
;                     if (kt) { float s8 = 0.f;
; #pragma unroll
;                         for (int e = 0; e < 4; ++e) { const unsigned ww = e == 0 ? w.x : (e == 1 ? w.y : (e == 2 ? w.z : w.w)); const float lo_ = __uint_as_float(ww << 16), hi_ = __uint_as_float(ww & 0xffff0000u);
;                             s8 = fmaf(lo_, lo_, s8); s8 = fmaf(hi_, hi_, s8); }
;                         s8 += sx(s8, 16, ln); s8 += sx(s8, 32, ln);
;                         km[ai][bj] = fmaxf(km[ai][bj], s8); } }
;                 if (m & 1) asm volatile("" ::: "memory"); }
	v_add_u32_e32 v233, 0x18000, v232
	v_cvt_pk_bf16_f32 v206, v94, v95
	v_cvt_pk_bf16_f32 v207, v96, v97
	v_cvt_pk_bf16_f32 v208, v90, v91
	v_cvt_pk_bf16_f32 v209, v92, v93
	v_cvt_pk_bf16_f32 v210, v86, v87
	v_cvt_pk_bf16_f32 v211, v88, v89
	v_cvt_pk_bf16_f32 v212, v82, v83
	v_cvt_pk_bf16_f32 v213, v84, v85
	global_store_dwordx4 v232, v[206:209], s[94:95]
	global_store_dwordx4 v232, v[210:213], s[94:95] offset:256
	v_mul_f32_e32 v78, v78, v197
	v_mul_f32_e32 v79, v79, v197
	v_mul_f32_e32 v80, v80, v197
	v_mul_f32_e32 v81, v81, v197
	v_mul_f32_e32 v74, v74, v197
	v_mul_f32_e32 v75, v75, v197
	v_mul_f32_e32 v76, v76, v197
	v_mul_f32_e32 v77, v77, v197
	v_mul_f32_e32 v70, v70, v197
	v_mul_f32_e32 v71, v71, v197
	v_mul_f32_e32 v72, v72, v197
	v_mul_f32_e32 v73, v73, v197
	v_mul_f32_e32 v66, v66, v197
	v_mul_f32_e32 v67, v67, v197
	v_mul_f32_e32 v68, v68, v197
	v_mul_f32_e32 v69, v69, v197
	v_add_u32_e32 v232, 0x78000, v233
	v_cvt_pk_bf16_f32 v224, v78, v79
	v_cvt_pk_bf16_f32 v225, v80, v81
	v_cvt_pk_bf16_f32 v226, v74, v75
	v_cvt_pk_bf16_f32 v227, v76, v77
	v_cvt_pk_bf16_f32 v228, v70, v71
	v_cvt_pk_bf16_f32 v229, v72, v73
	v_cvt_pk_bf16_f32 v230, v66, v67
	v_cvt_pk_bf16_f32 v231, v68, v69
	global_store_dwordx4 v233, v[224:227], s[94:95]
	global_store_dwordx4 v233, v[228:231], s[94:95] offset:256
	v_mul_f32_e32 v62, v62, v198
	v_mul_f32_e32 v63, v63, v198
	v_mul_f32_e32 v64, v64, v198
	v_mul_f32_e32 v65, v65, v198
	v_mul_f32_e32 v58, v58, v198
	v_mul_f32_e32 v59, v59, v198
	v_mul_f32_e32 v60, v60, v198
	v_mul_f32_e32 v61, v61, v198
	v_mul_f32_e32 v54, v54, v198
	v_mul_f32_e32 v55, v55, v198
	v_mul_f32_e32 v56, v56, v198
	v_mul_f32_e32 v57, v57, v198
	v_mul_f32_e32 v50, v50, v198
	v_mul_f32_e32 v51, v51, v198
	v_mul_f32_e32 v52, v52, v198
	v_mul_f32_e32 v53, v53, v198
	v_add_u32_e32 v233, 0x18000, v232
	v_cvt_pk_bf16_f32 v206, v62, v63
	v_cvt_pk_bf16_f32 v207, v64, v65
	v_cvt_pk_bf16_f32 v208, v58, v59
	v_cvt_pk_bf16_f32 v209, v60, v61
	v_cvt_pk_bf16_f32 v210, v54, v55
	v_cvt_pk_bf16_f32 v211, v56, v57
	v_cvt_pk_bf16_f32 v212, v50, v51
	v_cvt_pk_bf16_f32 v213, v52, v53
	global_store_dwordx4 v232, v[206:209], s[94:95]
	global_store_dwordx4 v232, v[210:213], s[94:95] offset:256
	v_mul_f32_e32 v46, v46, v199
	v_mul_f32_e32 v47, v47, v199
	v_mul_f32_e32 v48, v48, v199
	v_mul_f32_e32 v49, v49, v199
	v_mul_f32_e32 v42, v42, v199
	v_mul_f32_e32 v43, v43, v199
	v_mul_f32_e32 v44, v44, v199
	v_mul_f32_e32 v45, v45, v199
	v_mul_f32_e32 v38, v38, v199
	v_mul_f32_e32 v39, v39, v199
	v_mul_f32_e32 v40, v40, v199
	v_mul_f32_e32 v41, v41, v199
	v_mul_f32_e32 v34, v34, v199
	v_mul_f32_e32 v35, v35, v199
	v_mul_f32_e32 v36, v36, v199
	v_mul_f32_e32 v37, v37, v199
	v_add_u32_e32 v232, 0x18000, v233
	v_cvt_pk_bf16_f32 v224, v46, v47
	v_cvt_pk_bf16_f32 v225, v48, v49
	v_cvt_pk_bf16_f32 v226, v42, v43
	v_cvt_pk_bf16_f32 v227, v44, v45
	v_cvt_pk_bf16_f32 v228, v38, v39
	v_cvt_pk_bf16_f32 v229, v40, v41
	v_cvt_pk_bf16_f32 v230, v34, v35
	v_cvt_pk_bf16_f32 v231, v36, v37
	global_store_dwordx4 v233, v[224:227], s[94:95]
	global_store_dwordx4 v233, v[228:231], s[94:95] offset:256
	v_mul_f32_e32 v30, v30, v200
	v_mul_f32_e32 v31, v31, v200
	v_mul_f32_e32 v32, v32, v200
	v_mul_f32_e32 v33, v33, v200
	v_mul_f32_e32 v26, v26, v200
	v_mul_f32_e32 v27, v27, v200
	v_mul_f32_e32 v28, v28, v200
	v_mul_f32_e32 v29, v29, v200
	v_mul_f32_e32 v22, v22, v200
	v_mul_f32_e32 v23, v23, v200
	v_mul_f32_e32 v24, v24, v200
	v_mul_f32_e32 v25, v25, v200
	v_mul_f32_e32 v18, v18, v200
	v_mul_f32_e32 v19, v19, v200
	v_mul_f32_e32 v20, v20, v200
	v_mul_f32_e32 v21, v21, v200
	v_add_u32_e32 v233, 0x18000, v232
	v_cvt_pk_bf16_f32 v206, v30, v31
	v_cvt_pk_bf16_f32 v207, v32, v33
	v_cvt_pk_bf16_f32 v208, v26, v27
	v_cvt_pk_bf16_f32 v209, v28, v29
	v_cvt_pk_bf16_f32 v210, v22, v23
	v_cvt_pk_bf16_f32 v211, v24, v25
	v_cvt_pk_bf16_f32 v212, v18, v19
	v_cvt_pk_bf16_f32 v213, v20, v21
	global_store_dwordx4 v232, v[206:209], s[94:95]
	global_store_dwordx4 v232, v[210:213], s[94:95] offset:256
	v_mul_f32_e32 v14, v14, v201
	v_mul_f32_e32 v15, v15, v201
	v_mul_f32_e32 v16, v16, v201
	v_mul_f32_e32 v17, v17, v201
	v_mul_f32_e32 v10, v10, v201
	v_mul_f32_e32 v11, v11, v201
	v_mul_f32_e32 v12, v12, v201
	v_mul_f32_e32 v13, v13, v201
	v_mul_f32_e32 v6, v6, v201
	v_mul_f32_e32 v7, v7, v201
	v_mul_f32_e32 v8, v8, v201
	v_mul_f32_e32 v9, v9, v201
	v_mul_f32_e32 v2, v2, v201
	v_mul_f32_e32 v3, v3, v201
	v_mul_f32_e32 v4, v4, v201
	v_mul_f32_e32 v5, v5, v201
	v_cvt_pk_bf16_f32 v224, v14, v15
	v_cvt_pk_bf16_f32 v225, v16, v17
	v_cvt_pk_bf16_f32 v226, v10, v11
	v_cvt_pk_bf16_f32 v227, v12, v13
	v_cvt_pk_bf16_f32 v228, v6, v7
	v_cvt_pk_bf16_f32 v229, v8, v9
	v_cvt_pk_bf16_f32 v230, v2, v3
	v_cvt_pk_bf16_f32 v231, v4, v5
	global_store_dwordx4 v233, v[224:227], s[94:95]
	global_store_dwordx4 v233, v[228:231], s[94:95] offset:256
	s_branch .LBB0_598
.Lqkv_old:
	s_and_b64 vcc, exec, s[44:45]
	s_movk_i32 s10, 0x1800
	s_mov_b32 s11, 0xf800000
	s_cbranch_vccz .LBB0_556
	s_barrier
